# barrier: TOP arrival counter doubles as release flag (poll TOP >= (round+1)*nx), no TOPGEN/XGEN hops; with early inv
# speedup vs baseline: 1.0139x; 1.0021x over previous
; __device__ __forceinline__ unsigned xb_ld(unsigned* p)              { return __hip_atomic_load(p, __ATOMIC_RELAXED, __HIP_MEMORY_SCOPE_AGENT); }
; __device__ __forceinline__ unsigned xb_add(unsigned* p, unsigned v) { return __hip_atomic_fetch_add(p, v, __ATOMIC_RELAXED, __HIP_MEMORY_SCOPE_AGENT); }
; #define XB_SPIN(cond, bar) do { unsigned _sp = 0; while (cond) { __builtin_amdgcn_s_sleep(1); \
;     if ((++_sp & 255u) == 0u) { if (xb_ld(&(bar)[XB_TMO])) break; if (_sp > XB_SPIN_CAP) { atomicAdd(&(bar)[XB_TMO], 1u); break; } } } } while (0)
; __device__ __forceinline__ void xcd_barrier(const XcdBarrier& b) {
;     ...
;         const unsigned old = xb_add(&bar[XB_XSUB(b.x)], 1u);
;         const unsigned gen = old / nloc;
;         if (old + 1u == (gen + 1u) * nloc) {
;             __builtin_amdgcn_fence(__ATOMIC_RELEASE, "agent");
;             asm volatile("s_waitcnt vmcnt(0)" ::: "memory");
;             const unsigned og = xb_add(&bar[XB_TOP], 1u);
;             const unsigned tg = og / nx;
;             if (og + 1u == (tg + 1u) * nx) xb_add(&bar[XB_TOPGEN], 1u);
;             else XB_SPIN(xb_ld(&bar[XB_TOPGEN]) == tg, bar);
;             __builtin_amdgcn_fence(__ATOMIC_ACQUIRE, "agent");
;             xb_add(&bar[XB_XGEN(b.x)], 1u);
;             asm volatile("s_waitcnt vmcnt(0)" ::: "memory");
;         } else {
;             XB_SPIN(xb_ld(&bar[XB_XGEN(b.x)]) == gen, bar);
.LBB0_31:
	s_or_b64 exec, exec, s[10:11]
	v_cvt_f32_u32_e32 v5, v3
	s_waitcnt vmcnt(0)
	v_readfirstlane_b32 s8, v4
	v_sub_u32_e32 v4, 0, v3
	v_rcp_iflag_f32_e32 v5, v5
	v_add_u32_e32 v6, s8, v2
	v_mul_f32_e32 v5, 0x4f7ffffe, v5
	v_cvt_u32_f32_e32 v5, v5
	v_mul_lo_u32 v2, v4, v5
	v_mul_hi_u32 v2, v5, v2
	v_add_u32_e32 v2, v5, v2
	v_mul_hi_u32 v2, v6, v2
	v_mul_lo_u32 v4, v2, v3
	v_sub_u32_e32 v4, v6, v4
	v_add_u32_e32 v5, 1, v2
	v_cmp_ge_u32_e32 vcc, v4, v3
	s_nop 1
	v_cndmask_b32_e32 v2, v2, v5, vcc
	v_sub_u32_e32 v5, v4, v3
	v_cndmask_b32_e32 v4, v4, v5, vcc
	v_add_u32_e32 v5, 1, v2
	v_cmp_ge_u32_e32 vcc, v4, v3
	v_add_u32_e32 v4, 1, v6
	s_nop 0
	v_cndmask_b32_e32 v2, v2, v5, vcc
	v_mul_lo_u32 v5, v3, v2
	v_add_u32_e32 v3, v5, v3
	v_cmp_ne_u32_e32 vcc, v4, v3
	s_and_saveexec_b64 s[8:9], vcc
	s_xor_b64 s[8:9], exec, s[8:9]
	s_cbranch_execz .LBB0_45
	s_waitcnt lgkmcnt(0)
	buffer_inv sc1
	s_add_u32 s16, s60, 0x7400
	s_addc_u32 s17, s61, 0
	v_add_u32_e32 v2, 1, v2
	v_mul_lo_u32 v2, v2, v1
	v_mov_b32_e32 v1, 0
	global_load_dword v1, v1, s[16:17] sc1
	s_waitcnt vmcnt(0)
	v_cmp_lt_u32_e32 vcc, v1, v2
	s_and_saveexec_b64 s[10:11], vcc
	s_cbranch_execz .LBB0_44
	s_add_u32 s12, s60, 0x4200
	s_addc_u32 s13, s61, 0
	s_mov_b32 s14, 1
	s_mov_b64 s[18:19], 0
	v_mov_b32_e32 v1, 0
	s_branch .LBB0_35

; __device__ __forceinline__ unsigned xb_ld(unsigned* p)              { return __hip_atomic_load(p, __ATOMIC_RELAXED, __HIP_MEMORY_SCOPE_AGENT); }
; #define XB_SPIN(cond, bar) do { unsigned _sp = 0; while (cond) { __builtin_amdgcn_s_sleep(1); \
;     if ((++_sp & 255u) == 0u) { if (xb_ld(&(bar)[XB_TMO])) break; if (_sp > XB_SPIN_CAP) { atomicAdd(&(bar)[XB_TMO], 1u); break; } } } } while (0)
; __device__ __forceinline__ void xcd_barrier(const XcdBarrier& b) {
;     ...
;             XB_SPIN(xb_ld(&bar[XB_XGEN(b.x)]) == gen, bar);
;             __builtin_amdgcn_fence(__ATOMIC_ACQUIRE, "agent");
.LBB0_37:
	global_load_dword v3, v1, s[16:17] sc1
	s_add_i32 s14, s14, 1
	s_mov_b64 s[24:25], -1
	s_waitcnt vmcnt(0)
	v_cmp_ge_u32_e32 vcc, v3, v2
	s_orn2_b64 s[22:23], vcc, exec
	s_branch .LBB0_34

; __device__ __forceinline__ unsigned xb_ld(unsigned* p)              { return __hip_atomic_load(p, __ATOMIC_RELAXED, __HIP_MEMORY_SCOPE_AGENT); }
; __device__ __forceinline__ unsigned xb_add(unsigned* p, unsigned v) { return __hip_atomic_fetch_add(p, v, __ATOMIC_RELAXED, __HIP_MEMORY_SCOPE_AGENT); }
; #define XB_SPIN(cond, bar) do { unsigned _sp = 0; while (cond) { __builtin_amdgcn_s_sleep(1); \
;     if ((++_sp & 255u) == 0u) { if (xb_ld(&(bar)[XB_TMO])) break; if (_sp > XB_SPIN_CAP) { atomicAdd(&(bar)[XB_TMO], 1u); break; } } } } while (0)
; __device__ __forceinline__ void xcd_barrier(const XcdBarrier& b) {
;     ...
;             const unsigned og = xb_add(&bar[XB_TOP], 1u);
;             const unsigned tg = og / nx;
;             if (og + 1u == (tg + 1u) * nx) xb_add(&bar[XB_TOPGEN], 1u);
;             else XB_SPIN(xb_ld(&bar[XB_TOPGEN]) == tg, bar);
.LBB0_48:
	s_or_b64 exec, exec, s[10:11]
	v_cvt_f32_u32_e32 v4, v1
	s_waitcnt vmcnt(0)
	v_readfirstlane_b32 s8, v3
	buffer_inv sc1
	s_add_u32 s10, s60, 0x7400
	s_addc_u32 s11, s61, 0
	v_rcp_iflag_f32_e32 v4, v4
	v_add_u32_e32 v2, s8, v2
	v_add_u32_e32 v5, 1, v2
	s_mov_b64 s[12:13], 0
	v_mul_f32_e32 v3, 0x4f7ffffe, v4
	v_cvt_u32_f32_e32 v3, v3
	v_sub_u32_e32 v4, 0, v1
	v_mul_lo_u32 v4, v4, v3
	v_mul_hi_u32 v4, v3, v4
	v_add_u32_e32 v3, v3, v4
	v_mul_hi_u32 v3, v2, v3
	v_mul_lo_u32 v4, v3, v1
	v_sub_u32_e32 v2, v2, v4
	v_add_u32_e32 v6, 1, v3
	v_cmp_ge_u32_e32 vcc, v2, v1
	v_sub_u32_e32 v4, v2, v1
	s_nop 0
	v_cndmask_b32_e32 v3, v3, v6, vcc
	v_cndmask_b32_e32 v2, v2, v4, vcc
	v_add_u32_e32 v4, 1, v3
	v_cmp_ge_u32_e32 vcc, v2, v1
	s_nop 1
	v_cndmask_b32_e32 v4, v3, v4, vcc
	v_mul_lo_u32 v2, v1, v4
	v_add_u32_e32 v1, v2, v1
	v_cmp_ne_u32_e32 vcc, v5, v1
	v_mov_b64_e32 v[2:3], s[10:11]
	s_and_saveexec_b64 s[8:9], vcc
	s_cbranch_execz .LBB0_60
	v_mov_b32_e32 v4, v1
	v_mov_b32_e32 v1, 0
	global_load_dword v2, v1, s[10:11] sc1
	s_mov_b64 s[18:19], 0
	s_waitcnt vmcnt(0)
	v_cmp_lt_u32_e32 vcc, v2, v4
	s_and_saveexec_b64 s[16:17], vcc
	s_cbranch_execz .LBB0_59
	s_add_u32 s12, s60, 0x4200
	s_addc_u32 s13, s61, 0
	s_mov_b32 s14, 1
	s_branch .LBB0_52

; __device__ __forceinline__ unsigned xb_ld(unsigned* p)              { return __hip_atomic_load(p, __ATOMIC_RELAXED, __HIP_MEMORY_SCOPE_AGENT); }
; #define XB_SPIN(cond, bar) do { unsigned _sp = 0; while (cond) { __builtin_amdgcn_s_sleep(1); \
;     if ((++_sp & 255u) == 0u) { if (xb_ld(&(bar)[XB_TMO])) break; if (_sp > XB_SPIN_CAP) { atomicAdd(&(bar)[XB_TMO], 1u); break; } } } } while (0)
; __device__ __forceinline__ void xcd_barrier(const XcdBarrier& b) {
;     ...
;             else XB_SPIN(xb_ld(&bar[XB_TOPGEN]) == tg, bar);
.LBB0_54:
	global_load_dword v2, v1, s[10:11] sc1
	s_add_i32 s14, s14, 1
	s_mov_b64 s[22:23], -1
	s_waitcnt vmcnt(0)
	v_cmp_ge_u32_e32 vcc, v2, v4
	s_orn2_b64 s[26:27], vcc, exec
	s_branch .LBB0_51

; __device__ __forceinline__ unsigned xb_ld(unsigned* p)              { return __hip_atomic_load(p, __ATOMIC_RELAXED, __HIP_MEMORY_SCOPE_AGENT); }
; __device__ __forceinline__ unsigned xb_add(unsigned* p, unsigned v) { return __hip_atomic_fetch_add(p, v, __ATOMIC_RELAXED, __HIP_MEMORY_SCOPE_AGENT); }
; #define XB_SPIN(cond, bar) do { unsigned _sp = 0; while (cond) { __builtin_amdgcn_s_sleep(1); \
;     if ((++_sp & 255u) == 0u) { if (xb_ld(&(bar)[XB_TMO])) break; if (_sp > XB_SPIN_CAP) { atomicAdd(&(bar)[XB_TMO], 1u); break; } } } } while (0)
; __device__ __forceinline__ void xcd_barrier(const XcdBarrier& b) {
;     ...
;         const unsigned old = xb_add(&bar[XB_XSUB(b.x)], 1u);
;         const unsigned gen = old / nloc;
;         if (old + 1u == (gen + 1u) * nloc) {
;             __builtin_amdgcn_fence(__ATOMIC_RELEASE, "agent");
;             asm volatile("s_waitcnt vmcnt(0)" ::: "memory");
;             const unsigned og = xb_add(&bar[XB_TOP], 1u);
;             const unsigned tg = og / nx;
;             if (og + 1u == (tg + 1u) * nx) xb_add(&bar[XB_TOPGEN], 1u);
;             else XB_SPIN(xb_ld(&bar[XB_TOPGEN]) == tg, bar);
;             __builtin_amdgcn_fence(__ATOMIC_ACQUIRE, "agent");
;             xb_add(&bar[XB_XGEN(b.x)], 1u);
;             asm volatile("s_waitcnt vmcnt(0)" ::: "memory");
;         } else {
;             XB_SPIN(xb_ld(&bar[XB_XGEN(b.x)]) == gen, bar);
.LBB0_119:
	s_or_b64 exec, exec, s[8:9]
	v_cvt_f32_u32_e32 v5, v3
	s_waitcnt vmcnt(0)
	v_readfirstlane_b32 s3, v4
	v_sub_u32_e32 v4, 0, v3
	v_rcp_iflag_f32_e32 v5, v5
	v_add_u32_e32 v6, s3, v2
	v_mul_f32_e32 v5, 0x4f7ffffe, v5
	v_cvt_u32_f32_e32 v5, v5
	v_mul_lo_u32 v2, v4, v5
	v_mul_hi_u32 v2, v5, v2
	v_add_u32_e32 v2, v5, v2
	v_mul_hi_u32 v2, v6, v2
	v_mul_lo_u32 v4, v2, v3
	v_sub_u32_e32 v4, v6, v4
	v_add_u32_e32 v5, 1, v2
	v_cmp_ge_u32_e32 vcc, v4, v3
	s_nop 1
	v_cndmask_b32_e32 v2, v2, v5, vcc
	v_sub_u32_e32 v5, v4, v3
	v_cndmask_b32_e32 v4, v4, v5, vcc
	v_add_u32_e32 v5, 1, v2
	v_cmp_ge_u32_e32 vcc, v4, v3
	v_add_u32_e32 v4, 1, v6
	s_nop 0
	v_cndmask_b32_e32 v2, v2, v5, vcc
	v_mul_lo_u32 v5, v3, v2
	v_add_u32_e32 v3, v5, v3
	v_cmp_ne_u32_e32 vcc, v4, v3
	s_and_saveexec_b64 s[6:7], vcc
	s_xor_b64 s[6:7], exec, s[6:7]
	s_cbranch_execz .LBB0_133
	s_waitcnt lgkmcnt(0)
	buffer_inv sc1
	s_add_u32 s12, s60, 0x7400
	s_addc_u32 s13, s61, 0
	v_add_u32_e32 v2, 1, v2
	v_mul_lo_u32 v2, v2, v1
	v_mov_b32_e32 v1, 0
	global_load_dword v1, v1, s[12:13] sc1
	s_waitcnt vmcnt(0)
	v_cmp_lt_u32_e32 vcc, v1, v2
	s_and_saveexec_b64 s[8:9], vcc
	s_cbranch_execz .LBB0_132
	s_add_u32 s10, s60, 0x4200
	s_addc_u32 s11, s61, 0
	s_mov_b32 s3, 1
	s_mov_b64 s[16:17], 0
	v_mov_b32_e32 v1, 0
	s_branch .LBB0_123

; __device__ __forceinline__ unsigned xb_ld(unsigned* p)              { return __hip_atomic_load(p, __ATOMIC_RELAXED, __HIP_MEMORY_SCOPE_AGENT); }
; #define XB_SPIN(cond, bar) do { unsigned _sp = 0; while (cond) { __builtin_amdgcn_s_sleep(1); \
;     if ((++_sp & 255u) == 0u) { if (xb_ld(&(bar)[XB_TMO])) break; if (_sp > XB_SPIN_CAP) { atomicAdd(&(bar)[XB_TMO], 1u); break; } } } } while (0)
; __device__ __forceinline__ void xcd_barrier(const XcdBarrier& b) {
;     ...
;             XB_SPIN(xb_ld(&bar[XB_XGEN(b.x)]) == gen, bar);
;             __builtin_amdgcn_fence(__ATOMIC_ACQUIRE, "agent");
.LBB0_125:
	global_load_dword v3, v1, s[12:13] sc1
	s_add_i32 s3, s3, 1
	s_mov_b64 s[28:29], -1
	s_waitcnt vmcnt(0)
	v_cmp_ge_u32_e32 vcc, v3, v2
	s_orn2_b64 s[26:27], vcc, exec
	s_branch .LBB0_122

; __device__ __forceinline__ unsigned xb_ld(unsigned* p)              { return __hip_atomic_load(p, __ATOMIC_RELAXED, __HIP_MEMORY_SCOPE_AGENT); }
; __device__ __forceinline__ unsigned xb_add(unsigned* p, unsigned v) { return __hip_atomic_fetch_add(p, v, __ATOMIC_RELAXED, __HIP_MEMORY_SCOPE_AGENT); }
; #define XB_SPIN(cond, bar) do { unsigned _sp = 0; while (cond) { __builtin_amdgcn_s_sleep(1); \
;     if ((++_sp & 255u) == 0u) { if (xb_ld(&(bar)[XB_TMO])) break; if (_sp > XB_SPIN_CAP) { atomicAdd(&(bar)[XB_TMO], 1u); break; } } } } while (0)
; __device__ __forceinline__ void xcd_barrier(const XcdBarrier& b) {
;     ...
;             const unsigned og = xb_add(&bar[XB_TOP], 1u);
;             const unsigned tg = og / nx;
;             if (og + 1u == (tg + 1u) * nx) xb_add(&bar[XB_TOPGEN], 1u);
;             else XB_SPIN(xb_ld(&bar[XB_TOPGEN]) == tg, bar);
.LBB0_136:
	s_or_b64 exec, exec, s[8:9]
	v_cvt_f32_u32_e32 v4, v1
	s_waitcnt vmcnt(0)
	v_readfirstlane_b32 s3, v3
	buffer_inv sc1
	s_add_u32 s8, s60, 0x7400
	s_addc_u32 s9, s61, 0
	v_rcp_iflag_f32_e32 v4, v4
	v_add_u32_e32 v2, s3, v2
	v_add_u32_e32 v5, 1, v2
	s_mov_b64 s[10:11], 0
	v_mul_f32_e32 v3, 0x4f7ffffe, v4
	v_cvt_u32_f32_e32 v3, v3
	v_sub_u32_e32 v4, 0, v1
	v_mul_lo_u32 v4, v4, v3
	v_mul_hi_u32 v4, v3, v4
	v_add_u32_e32 v3, v3, v4
	v_mul_hi_u32 v3, v2, v3
	v_mul_lo_u32 v4, v3, v1
	v_sub_u32_e32 v2, v2, v4
	v_add_u32_e32 v6, 1, v3
	v_cmp_ge_u32_e32 vcc, v2, v1
	v_sub_u32_e32 v4, v2, v1
	s_nop 0
	v_cndmask_b32_e32 v3, v3, v6, vcc
	v_cndmask_b32_e32 v2, v2, v4, vcc
	v_add_u32_e32 v4, 1, v3
	v_cmp_ge_u32_e32 vcc, v2, v1
	s_nop 1
	v_cndmask_b32_e32 v4, v3, v4, vcc
	v_mul_lo_u32 v2, v1, v4
	v_add_u32_e32 v1, v2, v1
	v_cmp_ne_u32_e32 vcc, v5, v1
	v_mov_b64_e32 v[2:3], s[8:9]
	s_and_saveexec_b64 s[6:7], vcc
	s_cbranch_execz .LBB0_148
	v_mov_b32_e32 v4, v1
	v_mov_b32_e32 v1, 0
	global_load_dword v2, v1, s[8:9] sc1
	s_mov_b64 s[16:17], 0
	s_waitcnt vmcnt(0)
	v_cmp_lt_u32_e32 vcc, v2, v4
	s_and_saveexec_b64 s[12:13], vcc
	s_cbranch_execz .LBB0_147
	s_add_u32 s10, s60, 0x4200
	s_addc_u32 s11, s61, 0
	s_mov_b32 s3, 1
	s_branch .LBB0_140

; __device__ __forceinline__ unsigned xb_ld(unsigned* p)              { return __hip_atomic_load(p, __ATOMIC_RELAXED, __HIP_MEMORY_SCOPE_AGENT); }
; #define XB_SPIN(cond, bar) do { unsigned _sp = 0; while (cond) { __builtin_amdgcn_s_sleep(1); \
;     if ((++_sp & 255u) == 0u) { if (xb_ld(&(bar)[XB_TMO])) break; if (_sp > XB_SPIN_CAP) { atomicAdd(&(bar)[XB_TMO], 1u); break; } } } } while (0)
; __device__ __forceinline__ void xcd_barrier(const XcdBarrier& b) {
;     ...
;             else XB_SPIN(xb_ld(&bar[XB_TOPGEN]) == tg, bar);
.LBB0_142:
	global_load_dword v2, v1, s[8:9] sc1
	s_add_i32 s3, s3, 1
	s_mov_b64 s[26:27], -1
	s_waitcnt vmcnt(0)
	v_cmp_ge_u32_e32 vcc, v2, v4
	s_orn2_b64 s[30:31], vcc, exec
	s_branch .LBB0_139

; __device__ __forceinline__ unsigned xb_ld(unsigned* p)              { return __hip_atomic_load(p, __ATOMIC_RELAXED, __HIP_MEMORY_SCOPE_AGENT); }
; __device__ __forceinline__ unsigned xb_add(unsigned* p, unsigned v) { return __hip_atomic_fetch_add(p, v, __ATOMIC_RELAXED, __HIP_MEMORY_SCOPE_AGENT); }
; #define XB_SPIN(cond, bar) do { unsigned _sp = 0; while (cond) { __builtin_amdgcn_s_sleep(1); \
;     if ((++_sp & 255u) == 0u) { if (xb_ld(&(bar)[XB_TMO])) break; if (_sp > XB_SPIN_CAP) { atomicAdd(&(bar)[XB_TMO], 1u); break; } } } } while (0)
; __device__ __forceinline__ void xcd_barrier(const XcdBarrier& b) {
;     ...
;         const unsigned old = xb_add(&bar[XB_XSUB(b.x)], 1u);
;         const unsigned gen = old / nloc;
;         if (old + 1u == (gen + 1u) * nloc) {
;             __builtin_amdgcn_fence(__ATOMIC_RELEASE, "agent");
;             asm volatile("s_waitcnt vmcnt(0)" ::: "memory");
;             const unsigned og = xb_add(&bar[XB_TOP], 1u);
;             const unsigned tg = og / nx;
;             if (og + 1u == (tg + 1u) * nx) xb_add(&bar[XB_TOPGEN], 1u);
;             else XB_SPIN(xb_ld(&bar[XB_TOPGEN]) == tg, bar);
;             __builtin_amdgcn_fence(__ATOMIC_ACQUIRE, "agent");
;             xb_add(&bar[XB_XGEN(b.x)], 1u);
;             asm volatile("s_waitcnt vmcnt(0)" ::: "memory");
;         } else {
;             XB_SPIN(xb_ld(&bar[XB_XGEN(b.x)]) == gen, bar);
.LBB0_191:
	s_or_b64 exec, exec, s[6:7]
	v_cvt_f32_u32_e32 v5, v3
	s_waitcnt vmcnt(0)
	v_readfirstlane_b32 s4, v4
	v_sub_u32_e32 v4, 0, v3
	v_rcp_iflag_f32_e32 v5, v5
	v_add_u32_e32 v6, s4, v2
	v_mul_f32_e32 v5, 0x4f7ffffe, v5
	v_cvt_u32_f32_e32 v5, v5
	v_mul_lo_u32 v2, v4, v5
	v_mul_hi_u32 v2, v5, v2
	v_add_u32_e32 v2, v5, v2
	v_mul_hi_u32 v2, v6, v2
	v_mul_lo_u32 v4, v2, v3
	v_sub_u32_e32 v4, v6, v4
	v_add_u32_e32 v5, 1, v2
	v_cmp_ge_u32_e32 vcc, v4, v3
	s_nop 1
	v_cndmask_b32_e32 v2, v2, v5, vcc
	v_sub_u32_e32 v5, v4, v3
	v_cndmask_b32_e32 v4, v4, v5, vcc
	v_add_u32_e32 v5, 1, v2
	v_cmp_ge_u32_e32 vcc, v4, v3
	v_add_u32_e32 v4, 1, v6
	s_nop 0
	v_cndmask_b32_e32 v2, v2, v5, vcc
	v_mul_lo_u32 v5, v3, v2
	v_add_u32_e32 v3, v5, v3
	v_cmp_ne_u32_e32 vcc, v4, v3
	s_and_saveexec_b64 s[4:5], vcc
	s_xor_b64 s[4:5], exec, s[4:5]
	s_cbranch_execz .LBB0_205
	s_waitcnt lgkmcnt(0)
	buffer_inv sc1
	s_add_u32 s8, s34, 0x3400
	s_addc_u32 s9, s35, 0
	v_add_u32_e32 v2, 1, v2
	v_mul_lo_u32 v2, v2, v1
	v_mov_b32_e32 v1, 0
	global_load_dword v1, v1, s[8:9] sc1
	s_waitcnt vmcnt(0)
	v_cmp_lt_u32_e32 vcc, v1, v2
	s_and_saveexec_b64 s[6:7], vcc
	s_cbranch_execz .LBB0_204
	s_mov_b32 s14, 1
	s_mov_b64 s[10:11], 0
	v_mov_b32_e32 v1, 0
	s_branch .LBB0_195

; __device__ __forceinline__ unsigned xb_ld(unsigned* p)              { return __hip_atomic_load(p, __ATOMIC_RELAXED, __HIP_MEMORY_SCOPE_AGENT); }
; #define XB_SPIN(cond, bar) do { unsigned _sp = 0; while (cond) { __builtin_amdgcn_s_sleep(1); \
;     if ((++_sp & 255u) == 0u) { if (xb_ld(&(bar)[XB_TMO])) break; if (_sp > XB_SPIN_CAP) { atomicAdd(&(bar)[XB_TMO], 1u); break; } } } } while (0)
; __device__ __forceinline__ void xcd_barrier(const XcdBarrier& b) {
;     ...
;             XB_SPIN(xb_ld(&bar[XB_XGEN(b.x)]) == gen, bar);
;             __builtin_amdgcn_fence(__ATOMIC_ACQUIRE, "agent");
.LBB0_197:
	global_load_dword v3, v1, s[8:9] sc1
	s_add_i32 s14, s14, 1
	s_mov_b64 s[28:29], -1
	s_waitcnt vmcnt(0)
	v_cmp_ge_u32_e32 vcc, v3, v2
	s_orn2_b64 s[26:27], vcc, exec
	s_branch .LBB0_194

; __device__ __forceinline__ unsigned xb_ld(unsigned* p)              { return __hip_atomic_load(p, __ATOMIC_RELAXED, __HIP_MEMORY_SCOPE_AGENT); }
; __device__ __forceinline__ unsigned xb_add(unsigned* p, unsigned v) { return __hip_atomic_fetch_add(p, v, __ATOMIC_RELAXED, __HIP_MEMORY_SCOPE_AGENT); }
; #define XB_SPIN(cond, bar) do { unsigned _sp = 0; while (cond) { __builtin_amdgcn_s_sleep(1); \
;     if ((++_sp & 255u) == 0u) { if (xb_ld(&(bar)[XB_TMO])) break; if (_sp > XB_SPIN_CAP) { atomicAdd(&(bar)[XB_TMO], 1u); break; } } } } while (0)
; __device__ __forceinline__ void xcd_barrier(const XcdBarrier& b) {
;     ...
;             const unsigned og = xb_add(&bar[XB_TOP], 1u);
;             const unsigned tg = og / nx;
;             if (og + 1u == (tg + 1u) * nx) xb_add(&bar[XB_TOPGEN], 1u);
;             else XB_SPIN(xb_ld(&bar[XB_TOPGEN]) == tg, bar);
.LBB0_208:
	s_or_b64 exec, exec, s[8:9]
	v_cvt_f32_u32_e32 v4, v1
	s_waitcnt vmcnt(0)
	v_readfirstlane_b32 s6, v3
	buffer_inv sc1
	s_add_u32 s8, s34, 0x3400
	s_addc_u32 s9, s35, 0
	v_rcp_iflag_f32_e32 v4, v4
	v_add_u32_e32 v2, s6, v2
	v_add_u32_e32 v5, 1, v2
	s_mov_b64 s[10:11], 0
	v_mul_f32_e32 v3, 0x4f7ffffe, v4
	v_cvt_u32_f32_e32 v3, v3
	v_sub_u32_e32 v4, 0, v1
	v_mul_lo_u32 v4, v4, v3
	v_mul_hi_u32 v4, v3, v4
	v_add_u32_e32 v3, v3, v4
	v_mul_hi_u32 v3, v2, v3
	v_mul_lo_u32 v4, v3, v1
	v_sub_u32_e32 v2, v2, v4
	v_add_u32_e32 v6, 1, v3
	v_cmp_ge_u32_e32 vcc, v2, v1
	v_sub_u32_e32 v4, v2, v1
	s_nop 0
	v_cndmask_b32_e32 v3, v3, v6, vcc
	v_cndmask_b32_e32 v2, v2, v4, vcc
	v_add_u32_e32 v4, 1, v3
	v_cmp_ge_u32_e32 vcc, v2, v1
	s_nop 1
	v_cndmask_b32_e32 v4, v3, v4, vcc
	v_mul_lo_u32 v2, v1, v4
	v_add_u32_e32 v1, v2, v1
	v_cmp_ne_u32_e32 vcc, v5, v1
	v_mov_b64_e32 v[2:3], s[8:9]
	s_and_saveexec_b64 s[6:7], vcc
	s_cbranch_execz .LBB0_220
	v_mov_b32_e32 v4, v1
	v_mov_b32_e32 v1, 0
	global_load_dword v2, v1, s[8:9] sc1
	s_mov_b64 s[26:27], 0
	s_waitcnt vmcnt(0)
	v_cmp_lt_u32_e32 vcc, v2, v4
	s_and_saveexec_b64 s[12:13], vcc
	s_cbranch_execz .LBB0_219
	s_add_u32 s10, s34, 0x200
	s_addc_u32 s11, s35, 0
	s_mov_b32 s14, 1
	s_branch .LBB0_212

; __device__ __forceinline__ unsigned xb_ld(unsigned* p)              { return __hip_atomic_load(p, __ATOMIC_RELAXED, __HIP_MEMORY_SCOPE_AGENT); }
; #define XB_SPIN(cond, bar) do { unsigned _sp = 0; while (cond) { __builtin_amdgcn_s_sleep(1); \
;     if ((++_sp & 255u) == 0u) { if (xb_ld(&(bar)[XB_TMO])) break; if (_sp > XB_SPIN_CAP) { atomicAdd(&(bar)[XB_TMO], 1u); break; } } } } while (0)
; __device__ __forceinline__ void xcd_barrier(const XcdBarrier& b) {
;     ...
;             else XB_SPIN(xb_ld(&bar[XB_TOPGEN]) == tg, bar);
.LBB0_214:
	global_load_dword v2, v1, s[8:9] sc1
	s_add_i32 s14, s14, 1
	s_mov_b64 s[30:31], -1
	s_waitcnt vmcnt(0)
	v_cmp_ge_u32_e32 vcc, v2, v4
	s_orn2_b64 s[48:49], vcc, exec
	s_branch .LBB0_211

; __device__ __forceinline__ unsigned xb_ld(unsigned* p)              { return __hip_atomic_load(p, __ATOMIC_RELAXED, __HIP_MEMORY_SCOPE_AGENT); }
; __device__ __forceinline__ unsigned xb_add(unsigned* p, unsigned v) { return __hip_atomic_fetch_add(p, v, __ATOMIC_RELAXED, __HIP_MEMORY_SCOPE_AGENT); }
; #define XB_SPIN(cond, bar) do { unsigned _sp = 0; while (cond) { __builtin_amdgcn_s_sleep(1); \
;     if ((++_sp & 255u) == 0u) { if (xb_ld(&(bar)[XB_TMO])) break; if (_sp > XB_SPIN_CAP) { atomicAdd(&(bar)[XB_TMO], 1u); break; } } } } while (0)
; __device__ __forceinline__ void xcd_barrier(const XcdBarrier& b) {
;     ...
;         const unsigned old = xb_add(&bar[XB_XSUB(b.x)], 1u);
;         const unsigned gen = old / nloc;
;         if (old + 1u == (gen + 1u) * nloc) {
;             __builtin_amdgcn_fence(__ATOMIC_RELEASE, "agent");
;             asm volatile("s_waitcnt vmcnt(0)" ::: "memory");
;             const unsigned og = xb_add(&bar[XB_TOP], 1u);
;             const unsigned tg = og / nx;
;             if (og + 1u == (tg + 1u) * nx) xb_add(&bar[XB_TOPGEN], 1u);
;             else XB_SPIN(xb_ld(&bar[XB_TOPGEN]) == tg, bar);
;             __builtin_amdgcn_fence(__ATOMIC_ACQUIRE, "agent");
;             xb_add(&bar[XB_XGEN(b.x)], 1u);
;             asm volatile("s_waitcnt vmcnt(0)" ::: "memory");
;         } else {
;             XB_SPIN(xb_ld(&bar[XB_XGEN(b.x)]) == gen, bar);
.LBB0_401:
	s_or_b64 exec, exec, s[8:9]
	v_cvt_f32_u32_e32 v5, v3
	s_waitcnt vmcnt(0)
	v_readfirstlane_b32 s6, v4
	v_sub_u32_e32 v4, 0, v3
	v_rcp_iflag_f32_e32 v5, v5
	v_add_u32_e32 v6, s6, v2
	v_mul_f32_e32 v5, 0x4f7ffffe, v5
	v_cvt_u32_f32_e32 v5, v5
	v_mul_lo_u32 v2, v4, v5
	v_mul_hi_u32 v2, v5, v2
	v_add_u32_e32 v2, v5, v2
	v_mul_hi_u32 v2, v6, v2
	v_mul_lo_u32 v4, v2, v3
	v_sub_u32_e32 v4, v6, v4
	v_add_u32_e32 v5, 1, v2
	v_cmp_ge_u32_e32 vcc, v4, v3
	s_nop 1
	v_cndmask_b32_e32 v2, v2, v5, vcc
	v_sub_u32_e32 v5, v4, v3
	v_cndmask_b32_e32 v4, v4, v5, vcc
	v_add_u32_e32 v5, 1, v2
	v_cmp_ge_u32_e32 vcc, v4, v3
	v_add_u32_e32 v4, 1, v6
	s_nop 0
	v_cndmask_b32_e32 v2, v2, v5, vcc
	v_mul_lo_u32 v5, v3, v2
	v_add_u32_e32 v3, v5, v3
	v_cmp_ne_u32_e32 vcc, v4, v3
	s_and_saveexec_b64 s[6:7], vcc
	s_xor_b64 s[6:7], exec, s[6:7]
	s_cbranch_execz .LBB0_415
	s_waitcnt lgkmcnt(0)
	buffer_inv sc1
	s_add_u32 s10, s34, 0x3400
	s_addc_u32 s11, s35, 0
	v_add_u32_e32 v2, 1, v2
	v_mul_lo_u32 v2, v2, v1
	v_mov_b32_e32 v1, 0
	global_load_dword v1, v1, s[10:11] sc1
	s_waitcnt vmcnt(0)
	v_cmp_lt_u32_e32 vcc, v1, v2
	s_and_saveexec_b64 s[8:9], vcc
	s_cbranch_execz .LBB0_414
	s_mov_b32 s14, 1
	s_mov_b64 s[12:13], 0
	v_mov_b32_e32 v1, 0
	s_branch .LBB0_405

; __device__ __forceinline__ unsigned xb_ld(unsigned* p)              { return __hip_atomic_load(p, __ATOMIC_RELAXED, __HIP_MEMORY_SCOPE_AGENT); }
; #define XB_SPIN(cond, bar) do { unsigned _sp = 0; while (cond) { __builtin_amdgcn_s_sleep(1); \
;     if ((++_sp & 255u) == 0u) { if (xb_ld(&(bar)[XB_TMO])) break; if (_sp > XB_SPIN_CAP) { atomicAdd(&(bar)[XB_TMO], 1u); break; } } } } while (0)
; __device__ __forceinline__ void xcd_barrier(const XcdBarrier& b) {
;     ...
;             XB_SPIN(xb_ld(&bar[XB_XGEN(b.x)]) == gen, bar);
;             __builtin_amdgcn_fence(__ATOMIC_ACQUIRE, "agent");
.LBB0_407:
	global_load_dword v3, v1, s[10:11] sc1
	s_add_i32 s14, s14, 1
	s_mov_b64 s[22:23], -1
	s_waitcnt vmcnt(0)
	v_cmp_ge_u32_e32 vcc, v3, v2
	s_orn2_b64 s[20:21], vcc, exec
	s_branch .LBB0_404

; __device__ __forceinline__ unsigned xb_ld(unsigned* p)              { return __hip_atomic_load(p, __ATOMIC_RELAXED, __HIP_MEMORY_SCOPE_AGENT); }
; __device__ __forceinline__ unsigned xb_add(unsigned* p, unsigned v) { return __hip_atomic_fetch_add(p, v, __ATOMIC_RELAXED, __HIP_MEMORY_SCOPE_AGENT); }
; #define XB_SPIN(cond, bar) do { unsigned _sp = 0; while (cond) { __builtin_amdgcn_s_sleep(1); \
;     if ((++_sp & 255u) == 0u) { if (xb_ld(&(bar)[XB_TMO])) break; if (_sp > XB_SPIN_CAP) { atomicAdd(&(bar)[XB_TMO], 1u); break; } } } } while (0)
; __device__ __forceinline__ void xcd_barrier(const XcdBarrier& b) {
;     ...
;             const unsigned og = xb_add(&bar[XB_TOP], 1u);
;             const unsigned tg = og / nx;
;             if (og + 1u == (tg + 1u) * nx) xb_add(&bar[XB_TOPGEN], 1u);
;             else XB_SPIN(xb_ld(&bar[XB_TOPGEN]) == tg, bar);
.LBB0_418:
	s_or_b64 exec, exec, s[8:9]
	v_cvt_f32_u32_e32 v4, v1
	s_waitcnt vmcnt(0)
	v_readfirstlane_b32 s6, v3
	buffer_inv sc1
	s_add_u32 s8, s34, 0x3400
	s_addc_u32 s9, s35, 0
	v_rcp_iflag_f32_e32 v4, v4
	v_add_u32_e32 v2, s6, v2
	v_add_u32_e32 v5, 1, v2
	s_mov_b64 s[10:11], 0
	v_mul_f32_e32 v3, 0x4f7ffffe, v4
	v_cvt_u32_f32_e32 v3, v3
	v_sub_u32_e32 v4, 0, v1
	v_mul_lo_u32 v4, v4, v3
	v_mul_hi_u32 v4, v3, v4
	v_add_u32_e32 v3, v3, v4
	v_mul_hi_u32 v3, v2, v3
	v_mul_lo_u32 v4, v3, v1
	v_sub_u32_e32 v2, v2, v4
	v_add_u32_e32 v6, 1, v3
	v_cmp_ge_u32_e32 vcc, v2, v1
	v_sub_u32_e32 v4, v2, v1
	s_nop 0
	v_cndmask_b32_e32 v3, v3, v6, vcc
	v_cndmask_b32_e32 v2, v2, v4, vcc
	v_add_u32_e32 v4, 1, v3
	v_cmp_ge_u32_e32 vcc, v2, v1
	s_nop 1
	v_cndmask_b32_e32 v4, v3, v4, vcc
	v_mul_lo_u32 v2, v1, v4
	v_add_u32_e32 v1, v2, v1
	v_cmp_ne_u32_e32 vcc, v5, v1
	v_mov_b64_e32 v[2:3], s[8:9]
	s_and_saveexec_b64 s[6:7], vcc
	s_cbranch_execz .LBB0_430
	v_mov_b32_e32 v4, v1
	v_mov_b32_e32 v1, 0
	global_load_dword v2, v1, s[8:9] sc1
	s_mov_b64 s[18:19], 0
	s_waitcnt vmcnt(0)
	v_cmp_lt_u32_e32 vcc, v2, v4
	s_and_saveexec_b64 s[12:13], vcc
	s_cbranch_execz .LBB0_429
	s_add_u32 s10, s34, 0x200
	s_addc_u32 s11, s35, 0
	s_mov_b32 s14, 1
	s_branch .LBB0_422

; __device__ __forceinline__ unsigned xb_ld(unsigned* p)              { return __hip_atomic_load(p, __ATOMIC_RELAXED, __HIP_MEMORY_SCOPE_AGENT); }
; #define XB_SPIN(cond, bar) do { unsigned _sp = 0; while (cond) { __builtin_amdgcn_s_sleep(1); \
;     if ((++_sp & 255u) == 0u) { if (xb_ld(&(bar)[XB_TMO])) break; if (_sp > XB_SPIN_CAP) { atomicAdd(&(bar)[XB_TMO], 1u); break; } } } } while (0)
; __device__ __forceinline__ void xcd_barrier(const XcdBarrier& b) {
;     ...
;             else XB_SPIN(xb_ld(&bar[XB_TOPGEN]) == tg, bar);
.LBB0_424:
	global_load_dword v2, v1, s[8:9] sc1
	s_add_i32 s14, s14, 1
	s_mov_b64 s[22:23], -1
	s_waitcnt vmcnt(0)
	v_cmp_ge_u32_e32 vcc, v2, v4
	s_orn2_b64 s[26:27], vcc, exec
	s_branch .LBB0_421

; __device__ __forceinline__ unsigned xb_ld(unsigned* p)              { return __hip_atomic_load(p, __ATOMIC_RELAXED, __HIP_MEMORY_SCOPE_AGENT); }
; __device__ __forceinline__ unsigned xb_add(unsigned* p, unsigned v) { return __hip_atomic_fetch_add(p, v, __ATOMIC_RELAXED, __HIP_MEMORY_SCOPE_AGENT); }
; #define XB_SPIN(cond, bar) do { unsigned _sp = 0; while (cond) { __builtin_amdgcn_s_sleep(1); \
;     if ((++_sp & 255u) == 0u) { if (xb_ld(&(bar)[XB_TMO])) break; if (_sp > XB_SPIN_CAP) { atomicAdd(&(bar)[XB_TMO], 1u); break; } } } } while (0)
; __device__ __forceinline__ void xcd_barrier(const XcdBarrier& b) {
;     ...
;         const unsigned old = xb_add(&bar[XB_XSUB(b.x)], 1u);
;         const unsigned gen = old / nloc;
;         if (old + 1u == (gen + 1u) * nloc) {
;             __builtin_amdgcn_fence(__ATOMIC_RELEASE, "agent");
;             asm volatile("s_waitcnt vmcnt(0)" ::: "memory");
;             const unsigned og = xb_add(&bar[XB_TOP], 1u);
;             const unsigned tg = og / nx;
;             if (og + 1u == (tg + 1u) * nx) xb_add(&bar[XB_TOPGEN], 1u);
;             else XB_SPIN(xb_ld(&bar[XB_TOPGEN]) == tg, bar);
;             __builtin_amdgcn_fence(__ATOMIC_ACQUIRE, "agent");
;             xb_add(&bar[XB_XGEN(b.x)], 1u);
;             asm volatile("s_waitcnt vmcnt(0)" ::: "memory");
;         } else {
;             XB_SPIN(xb_ld(&bar[XB_XGEN(b.x)]) == gen, bar);
.LBB0_475:
	s_or_b64 exec, exec, s[6:7]
	v_cvt_f32_u32_e32 v5, v3
	s_waitcnt vmcnt(0)
	v_readfirstlane_b32 s4, v4
	v_sub_u32_e32 v4, 0, v3
	v_rcp_iflag_f32_e32 v5, v5
	v_add_u32_e32 v6, s4, v2
	v_mul_f32_e32 v5, 0x4f7ffffe, v5
	v_cvt_u32_f32_e32 v5, v5
	v_mul_lo_u32 v2, v4, v5
	v_mul_hi_u32 v2, v5, v2
	v_add_u32_e32 v2, v5, v2
	v_mul_hi_u32 v2, v6, v2
	v_mul_lo_u32 v4, v2, v3
	v_sub_u32_e32 v4, v6, v4
	v_add_u32_e32 v5, 1, v2
	v_cmp_ge_u32_e32 vcc, v4, v3
	s_nop 1
	v_cndmask_b32_e32 v2, v2, v5, vcc
	v_sub_u32_e32 v5, v4, v3
	v_cndmask_b32_e32 v4, v4, v5, vcc
	v_add_u32_e32 v5, 1, v2
	v_cmp_ge_u32_e32 vcc, v4, v3
	v_add_u32_e32 v4, 1, v6
	s_nop 0
	v_cndmask_b32_e32 v2, v2, v5, vcc
	v_mul_lo_u32 v5, v3, v2
	v_add_u32_e32 v3, v5, v3
	v_cmp_ne_u32_e32 vcc, v4, v3
	s_and_saveexec_b64 s[4:5], vcc
	s_xor_b64 s[4:5], exec, s[4:5]
	s_cbranch_execz .LBB0_489
	s_waitcnt lgkmcnt(0)
	buffer_inv sc1
	s_add_u32 s8, s34, 0x3400
	s_addc_u32 s9, s35, 0
	v_add_u32_e32 v2, 1, v2
	v_mul_lo_u32 v2, v2, v1
	v_mov_b32_e32 v1, 0
	global_load_dword v1, v1, s[8:9] sc1
	s_waitcnt vmcnt(0)
	v_cmp_lt_u32_e32 vcc, v1, v2
	s_and_saveexec_b64 s[6:7], vcc
	s_cbranch_execz .LBB0_488
	s_mov_b32 s11, 1
	s_mov_b64 s[22:23], 0
	v_mov_b32_e32 v1, 0
	s_branch .LBB0_479

; __device__ __forceinline__ unsigned xb_ld(unsigned* p)              { return __hip_atomic_load(p, __ATOMIC_RELAXED, __HIP_MEMORY_SCOPE_AGENT); }
; #define XB_SPIN(cond, bar) do { unsigned _sp = 0; while (cond) { __builtin_amdgcn_s_sleep(1); \
;     if ((++_sp & 255u) == 0u) { if (xb_ld(&(bar)[XB_TMO])) break; if (_sp > XB_SPIN_CAP) { atomicAdd(&(bar)[XB_TMO], 1u); break; } } } } while (0)
; __device__ __forceinline__ void xcd_barrier(const XcdBarrier& b) {
;     ...
;             XB_SPIN(xb_ld(&bar[XB_XGEN(b.x)]) == gen, bar);
;             __builtin_amdgcn_fence(__ATOMIC_ACQUIRE, "agent");
.LBB0_481:
	global_load_dword v3, v1, s[8:9] sc1
	s_add_i32 s11, s11, 1
	s_mov_b64 s[28:29], -1
	s_waitcnt vmcnt(0)
	v_cmp_ge_u32_e32 vcc, v3, v2
	s_orn2_b64 s[26:27], vcc, exec
	s_branch .LBB0_478

; __device__ __forceinline__ unsigned xb_ld(unsigned* p)              { return __hip_atomic_load(p, __ATOMIC_RELAXED, __HIP_MEMORY_SCOPE_AGENT); }
; __device__ __forceinline__ unsigned xb_add(unsigned* p, unsigned v) { return __hip_atomic_fetch_add(p, v, __ATOMIC_RELAXED, __HIP_MEMORY_SCOPE_AGENT); }
; #define XB_SPIN(cond, bar) do { unsigned _sp = 0; while (cond) { __builtin_amdgcn_s_sleep(1); \
;     if ((++_sp & 255u) == 0u) { if (xb_ld(&(bar)[XB_TMO])) break; if (_sp > XB_SPIN_CAP) { atomicAdd(&(bar)[XB_TMO], 1u); break; } } } } while (0)
; __device__ __forceinline__ void xcd_barrier(const XcdBarrier& b) {
;     ...
;             const unsigned og = xb_add(&bar[XB_TOP], 1u);
;             const unsigned tg = og / nx;
;             if (og + 1u == (tg + 1u) * nx) xb_add(&bar[XB_TOPGEN], 1u);
;             else XB_SPIN(xb_ld(&bar[XB_TOPGEN]) == tg, bar);
.LBB0_492:
	s_or_b64 exec, exec, s[8:9]
	v_cvt_f32_u32_e32 v4, v1
	s_waitcnt vmcnt(0)
	v_readfirstlane_b32 s6, v3
	buffer_inv sc1
	s_add_u32 s8, s34, 0x3400
	s_addc_u32 s9, s35, 0
	v_rcp_iflag_f32_e32 v4, v4
	v_add_u32_e32 v2, s6, v2
	v_add_u32_e32 v5, 1, v2
	s_mov_b64 s[22:23], 0
	v_mul_f32_e32 v3, 0x4f7ffffe, v4
	v_cvt_u32_f32_e32 v3, v3
	v_sub_u32_e32 v4, 0, v1
	v_mul_lo_u32 v4, v4, v3
	v_mul_hi_u32 v4, v3, v4
	v_add_u32_e32 v3, v3, v4
	v_mul_hi_u32 v3, v2, v3
	v_mul_lo_u32 v4, v3, v1
	v_sub_u32_e32 v2, v2, v4
	v_add_u32_e32 v6, 1, v3
	v_cmp_ge_u32_e32 vcc, v2, v1
	v_sub_u32_e32 v4, v2, v1
	s_nop 0
	v_cndmask_b32_e32 v3, v3, v6, vcc
	v_cndmask_b32_e32 v2, v2, v4, vcc
	v_add_u32_e32 v4, 1, v3
	v_cmp_ge_u32_e32 vcc, v2, v1
	s_nop 1
	v_cndmask_b32_e32 v4, v3, v4, vcc
	v_mul_lo_u32 v2, v1, v4
	v_add_u32_e32 v1, v2, v1
	v_cmp_ne_u32_e32 vcc, v5, v1
	v_mov_b64_e32 v[2:3], s[8:9]
	s_and_saveexec_b64 s[6:7], vcc
	s_cbranch_execz .LBB0_504
	v_mov_b32_e32 v4, v1
	v_mov_b32_e32 v1, 0
	global_load_dword v2, v1, s[8:9] sc1
	s_mov_b64 s[26:27], 0
	s_waitcnt vmcnt(0)
	v_cmp_lt_u32_e32 vcc, v2, v4
	s_and_saveexec_b64 s[24:25], vcc
	s_cbranch_execz .LBB0_503
	s_add_u32 s22, s34, 0x200
	s_addc_u32 s23, s35, 0
	s_mov_b32 s11, 1
	s_branch .LBB0_496

; __device__ __forceinline__ unsigned xb_ld(unsigned* p)              { return __hip_atomic_load(p, __ATOMIC_RELAXED, __HIP_MEMORY_SCOPE_AGENT); }
; #define XB_SPIN(cond, bar) do { unsigned _sp = 0; while (cond) { __builtin_amdgcn_s_sleep(1); \
;     if ((++_sp & 255u) == 0u) { if (xb_ld(&(bar)[XB_TMO])) break; if (_sp > XB_SPIN_CAP) { atomicAdd(&(bar)[XB_TMO], 1u); break; } } } } while (0)
; __device__ __forceinline__ void xcd_barrier(const XcdBarrier& b) {
;     ...
;             else XB_SPIN(xb_ld(&bar[XB_TOPGEN]) == tg, bar);
.LBB0_498:
	global_load_dword v2, v1, s[8:9] sc1
	s_add_i32 s11, s11, 1
	s_mov_b64 s[30:31], -1
	s_waitcnt vmcnt(0)
	v_cmp_ge_u32_e32 vcc, v2, v4
	s_orn2_b64 s[38:39], vcc, exec
	s_branch .LBB0_495

; __device__ __forceinline__ unsigned xb_ld(unsigned* p)              { return __hip_atomic_load(p, __ATOMIC_RELAXED, __HIP_MEMORY_SCOPE_AGENT); }
; __device__ __forceinline__ unsigned xb_add(unsigned* p, unsigned v) { return __hip_atomic_fetch_add(p, v, __ATOMIC_RELAXED, __HIP_MEMORY_SCOPE_AGENT); }
; #define XB_SPIN(cond, bar) do { unsigned _sp = 0; while (cond) { __builtin_amdgcn_s_sleep(1); \
;     if ((++_sp & 255u) == 0u) { if (xb_ld(&(bar)[XB_TMO])) break; if (_sp > XB_SPIN_CAP) { atomicAdd(&(bar)[XB_TMO], 1u); break; } } } } while (0)
; __device__ __forceinline__ void xcd_barrier(const XcdBarrier& b) {
;     ...
;         const unsigned old = xb_add(&bar[XB_XSUB(b.x)], 1u);
;         const unsigned gen = old / nloc;
;         if (old + 1u == (gen + 1u) * nloc) {
;             __builtin_amdgcn_fence(__ATOMIC_RELEASE, "agent");
;             asm volatile("s_waitcnt vmcnt(0)" ::: "memory");
;             const unsigned og = xb_add(&bar[XB_TOP], 1u);
;             const unsigned tg = og / nx;
;             if (og + 1u == (tg + 1u) * nx) xb_add(&bar[XB_TOPGEN], 1u);
;             else XB_SPIN(xb_ld(&bar[XB_TOPGEN]) == tg, bar);
;             __builtin_amdgcn_fence(__ATOMIC_ACQUIRE, "agent");
;             xb_add(&bar[XB_XGEN(b.x)], 1u);
;             asm volatile("s_waitcnt vmcnt(0)" ::: "memory");
;         } else {
;             XB_SPIN(xb_ld(&bar[XB_XGEN(b.x)]) == gen, bar);
.LBB0_580:
	s_or_b64 exec, exec, s[6:7]
	v_cvt_f32_u32_e32 v5, v3
	s_waitcnt vmcnt(0)
	v_readfirstlane_b32 s4, v4
	v_sub_u32_e32 v4, 0, v3
	v_rcp_iflag_f32_e32 v5, v5
	v_add_u32_e32 v6, s4, v2
	v_mul_f32_e32 v5, 0x4f7ffffe, v5
	v_cvt_u32_f32_e32 v5, v5
	v_mul_lo_u32 v2, v4, v5
	v_mul_hi_u32 v2, v5, v2
	v_add_u32_e32 v2, v5, v2
	v_mul_hi_u32 v2, v6, v2
	v_mul_lo_u32 v4, v2, v3
	v_sub_u32_e32 v4, v6, v4
	v_add_u32_e32 v5, 1, v2
	v_cmp_ge_u32_e32 vcc, v4, v3
	s_nop 1
	v_cndmask_b32_e32 v2, v2, v5, vcc
	v_sub_u32_e32 v5, v4, v3
	v_cndmask_b32_e32 v4, v4, v5, vcc
	v_add_u32_e32 v5, 1, v2
	v_cmp_ge_u32_e32 vcc, v4, v3
	v_add_u32_e32 v4, 1, v6
	s_nop 0
	v_cndmask_b32_e32 v2, v2, v5, vcc
	v_mul_lo_u32 v5, v3, v2
	v_add_u32_e32 v3, v5, v3
	v_cmp_ne_u32_e32 vcc, v4, v3
	s_and_saveexec_b64 s[4:5], vcc
	s_xor_b64 s[4:5], exec, s[4:5]
	s_cbranch_execz .LBB0_594
	s_waitcnt lgkmcnt(0)
	buffer_inv sc1
	s_add_u32 s8, s34, 0x3400
	s_addc_u32 s9, s35, 0
	v_add_u32_e32 v2, 1, v2
	v_mul_lo_u32 v2, v2, v1
	v_mov_b32_e32 v1, 0
	global_load_dword v1, v1, s[8:9] sc1
	s_waitcnt vmcnt(0)
	v_cmp_lt_u32_e32 vcc, v1, v2
	s_and_saveexec_b64 s[6:7], vcc
	s_cbranch_execz .LBB0_593
	s_mov_b32 s11, 1
	s_mov_b64 s[20:21], 0
	v_mov_b32_e32 v1, 0
	s_branch .LBB0_584

; __device__ __forceinline__ unsigned xb_ld(unsigned* p)              { return __hip_atomic_load(p, __ATOMIC_RELAXED, __HIP_MEMORY_SCOPE_AGENT); }
; __device__ __forceinline__ unsigned xb_add(unsigned* p, unsigned v) { return __hip_atomic_fetch_add(p, v, __ATOMIC_RELAXED, __HIP_MEMORY_SCOPE_AGENT); }
; #define XB_SPIN(cond, bar) do { unsigned _sp = 0; while (cond) { __builtin_amdgcn_s_sleep(1); \
;     if ((++_sp & 255u) == 0u) { if (xb_ld(&(bar)[XB_TMO])) break; if (_sp > XB_SPIN_CAP) { atomicAdd(&(bar)[XB_TMO], 1u); break; } } } } while (0)
; __device__ __forceinline__ void xcd_barrier(const XcdBarrier& b) {
;     ...
;             const unsigned og = xb_add(&bar[XB_TOP], 1u);
;             const unsigned tg = og / nx;
;             if (og + 1u == (tg + 1u) * nx) xb_add(&bar[XB_TOPGEN], 1u);
;             else XB_SPIN(xb_ld(&bar[XB_TOPGEN]) == tg, bar);
.LBB0_597:
	s_or_b64 exec, exec, s[8:9]
	v_cvt_f32_u32_e32 v4, v1
	s_waitcnt vmcnt(0)
	v_readfirstlane_b32 s6, v3
	buffer_inv sc1
	s_add_u32 s8, s34, 0x3400
	s_addc_u32 s9, s35, 0
	v_rcp_iflag_f32_e32 v4, v4
	v_add_u32_e32 v2, s6, v2
	v_add_u32_e32 v5, 1, v2
	s_mov_b64 s[20:21], 0
	v_mul_f32_e32 v3, 0x4f7ffffe, v4
	v_cvt_u32_f32_e32 v3, v3
	v_sub_u32_e32 v4, 0, v1
	v_mul_lo_u32 v4, v4, v3
	v_mul_hi_u32 v4, v3, v4
	v_add_u32_e32 v3, v3, v4
	v_mul_hi_u32 v3, v2, v3
	v_mul_lo_u32 v4, v3, v1
	v_sub_u32_e32 v2, v2, v4
	v_add_u32_e32 v6, 1, v3
	v_cmp_ge_u32_e32 vcc, v2, v1
	v_sub_u32_e32 v4, v2, v1
	s_nop 0
	v_cndmask_b32_e32 v3, v3, v6, vcc
	v_cndmask_b32_e32 v2, v2, v4, vcc
	v_add_u32_e32 v4, 1, v3
	v_cmp_ge_u32_e32 vcc, v2, v1
	s_nop 1
	v_cndmask_b32_e32 v4, v3, v4, vcc
	v_mul_lo_u32 v2, v1, v4
	v_add_u32_e32 v1, v2, v1
	v_cmp_ne_u32_e32 vcc, v5, v1
	v_mov_b64_e32 v[2:3], s[8:9]
	s_and_saveexec_b64 s[6:7], vcc
	s_cbranch_execz .LBB0_609
	v_mov_b32_e32 v4, v1
	v_mov_b32_e32 v1, 0
	global_load_dword v2, v1, s[8:9] sc1
	s_mov_b64 s[26:27], 0
	s_waitcnt vmcnt(0)
	v_cmp_lt_u32_e32 vcc, v2, v4
	s_and_saveexec_b64 s[24:25], vcc
	s_cbranch_execz .LBB0_608
	s_add_u32 s20, s34, 0x200
	s_addc_u32 s21, s35, 0
	s_mov_b32 s11, 1
	s_branch .LBB0_601

; __device__ __forceinline__ unsigned xb_ld(unsigned* p)              { return __hip_atomic_load(p, __ATOMIC_RELAXED, __HIP_MEMORY_SCOPE_AGENT); }
; __device__ __forceinline__ unsigned xb_add(unsigned* p, unsigned v) { return __hip_atomic_fetch_add(p, v, __ATOMIC_RELAXED, __HIP_MEMORY_SCOPE_AGENT); }
; #define XB_SPIN(cond, bar) do { unsigned _sp = 0; while (cond) { __builtin_amdgcn_s_sleep(1); \
;     if ((++_sp & 255u) == 0u) { if (xb_ld(&(bar)[XB_TMO])) break; if (_sp > XB_SPIN_CAP) { atomicAdd(&(bar)[XB_TMO], 1u); break; } } } } while (0)
; __device__ __forceinline__ void xcd_barrier(const XcdBarrier& b) {
;     ...
;         const unsigned old = xb_add(&bar[XB_XSUB(b.x)], 1u);
;         const unsigned gen = old / nloc;
;         if (old + 1u == (gen + 1u) * nloc) {
;             __builtin_amdgcn_fence(__ATOMIC_RELEASE, "agent");
;             asm volatile("s_waitcnt vmcnt(0)" ::: "memory");
;             const unsigned og = xb_add(&bar[XB_TOP], 1u);
;             const unsigned tg = og / nx;
;             if (og + 1u == (tg + 1u) * nx) xb_add(&bar[XB_TOPGEN], 1u);
;             else XB_SPIN(xb_ld(&bar[XB_TOPGEN]) == tg, bar);
;             __builtin_amdgcn_fence(__ATOMIC_ACQUIRE, "agent");
;             xb_add(&bar[XB_XGEN(b.x)], 1u);
;             asm volatile("s_waitcnt vmcnt(0)" ::: "memory");
;         } else {
;             XB_SPIN(xb_ld(&bar[XB_XGEN(b.x)]) == gen, bar);
.LBB0_656:
	s_or_b64 exec, exec, s[6:7]
	v_cvt_f32_u32_e32 v5, v3
	s_waitcnt vmcnt(0)
	v_readfirstlane_b32 s4, v4
	v_sub_u32_e32 v4, 0, v3
	v_rcp_iflag_f32_e32 v5, v5
	v_add_u32_e32 v6, s4, v2
	v_mul_f32_e32 v5, 0x4f7ffffe, v5
	v_cvt_u32_f32_e32 v5, v5
	v_mul_lo_u32 v2, v4, v5
	v_mul_hi_u32 v2, v5, v2
	v_add_u32_e32 v2, v5, v2
	v_mul_hi_u32 v2, v6, v2
	v_mul_lo_u32 v4, v2, v3
	v_sub_u32_e32 v4, v6, v4
	v_add_u32_e32 v5, 1, v2
	v_cmp_ge_u32_e32 vcc, v4, v3
	s_nop 1
	v_cndmask_b32_e32 v2, v2, v5, vcc
	v_sub_u32_e32 v5, v4, v3
	v_cndmask_b32_e32 v4, v4, v5, vcc
	v_add_u32_e32 v5, 1, v2
	v_cmp_ge_u32_e32 vcc, v4, v3
	v_add_u32_e32 v4, 1, v6
	s_nop 0
	v_cndmask_b32_e32 v2, v2, v5, vcc
	v_mul_lo_u32 v5, v3, v2
	v_add_u32_e32 v3, v5, v3
	v_cmp_ne_u32_e32 vcc, v4, v3
	s_and_saveexec_b64 s[4:5], vcc
	s_xor_b64 s[4:5], exec, s[4:5]
	s_cbranch_execz .LBB0_670
	s_waitcnt lgkmcnt(0)
	buffer_inv sc1
	s_add_u32 s8, s34, 0x3400
	s_addc_u32 s9, s35, 0
	v_add_u32_e32 v2, 1, v2
	v_mul_lo_u32 v2, v2, v1
	v_mov_b32_e32 v1, 0
	global_load_dword v1, v1, s[8:9] sc1
	s_waitcnt vmcnt(0)
	v_cmp_lt_u32_e32 vcc, v1, v2
	s_and_saveexec_b64 s[6:7], vcc
	s_cbranch_execz .LBB0_669
	s_mov_b32 s11, 1
	s_mov_b64 s[14:15], 0
	v_mov_b32_e32 v1, 0
	s_branch .LBB0_660

; __device__ __forceinline__ unsigned xb_ld(unsigned* p)              { return __hip_atomic_load(p, __ATOMIC_RELAXED, __HIP_MEMORY_SCOPE_AGENT); }
; #define XB_SPIN(cond, bar) do { unsigned _sp = 0; while (cond) { __builtin_amdgcn_s_sleep(1); \
;     if ((++_sp & 255u) == 0u) { if (xb_ld(&(bar)[XB_TMO])) break; if (_sp > XB_SPIN_CAP) { atomicAdd(&(bar)[XB_TMO], 1u); break; } } } } while (0)
; __device__ __forceinline__ void xcd_barrier(const XcdBarrier& b) {
;     ...
;             XB_SPIN(xb_ld(&bar[XB_XGEN(b.x)]) == gen, bar);
;             __builtin_amdgcn_fence(__ATOMIC_ACQUIRE, "agent");
.LBB0_662:
	global_load_dword v3, v1, s[8:9] sc1
	s_add_i32 s11, s11, 1
	s_mov_b64 s[24:25], -1
	s_waitcnt vmcnt(0)
	v_cmp_ge_u32_e32 vcc, v3, v2
	s_orn2_b64 s[22:23], vcc, exec
	s_branch .LBB0_659

; __device__ __forceinline__ unsigned xb_ld(unsigned* p)              { return __hip_atomic_load(p, __ATOMIC_RELAXED, __HIP_MEMORY_SCOPE_AGENT); }
; __device__ __forceinline__ unsigned xb_add(unsigned* p, unsigned v) { return __hip_atomic_fetch_add(p, v, __ATOMIC_RELAXED, __HIP_MEMORY_SCOPE_AGENT); }
; #define XB_SPIN(cond, bar) do { unsigned _sp = 0; while (cond) { __builtin_amdgcn_s_sleep(1); \
;     if ((++_sp & 255u) == 0u) { if (xb_ld(&(bar)[XB_TMO])) break; if (_sp > XB_SPIN_CAP) { atomicAdd(&(bar)[XB_TMO], 1u); break; } } } } while (0)
; __device__ __forceinline__ void xcd_barrier(const XcdBarrier& b) {
;     ...
;         const unsigned old = xb_add(&bar[XB_XSUB(b.x)], 1u);
;         const unsigned gen = old / nloc;
;         if (old + 1u == (gen + 1u) * nloc) {
;             __builtin_amdgcn_fence(__ATOMIC_RELEASE, "agent");
;             asm volatile("s_waitcnt vmcnt(0)" ::: "memory");
;             const unsigned og = xb_add(&bar[XB_TOP], 1u);
;             const unsigned tg = og / nx;
;             if (og + 1u == (tg + 1u) * nx) xb_add(&bar[XB_TOPGEN], 1u);
;             else XB_SPIN(xb_ld(&bar[XB_TOPGEN]) == tg, bar);
.LBB0_673:
	s_or_b64 exec, exec, s[6:7]
	v_cvt_f32_u32_e32 v4, v1
	s_waitcnt vmcnt(0)
	v_readfirstlane_b32 s4, v3
	buffer_inv sc1
	s_add_u32 s6, s34, 0x3400
	s_addc_u32 s7, s35, 0
	v_rcp_iflag_f32_e32 v4, v4
	v_add_u32_e32 v2, s4, v2
	v_add_u32_e32 v5, 1, v2
	s_mov_b64 s[8:9], 0
	v_mul_f32_e32 v3, 0x4f7ffffe, v4
	v_cvt_u32_f32_e32 v3, v3
	v_sub_u32_e32 v4, 0, v1
	v_mul_lo_u32 v4, v4, v3
	v_mul_hi_u32 v4, v3, v4
	v_add_u32_e32 v3, v3, v4
	v_mul_hi_u32 v3, v2, v3
	v_mul_lo_u32 v4, v3, v1
	v_sub_u32_e32 v2, v2, v4
	v_add_u32_e32 v6, 1, v3
	v_cmp_ge_u32_e32 vcc, v2, v1
	v_sub_u32_e32 v4, v2, v1
	s_nop 0
	v_cndmask_b32_e32 v3, v3, v6, vcc
	v_cndmask_b32_e32 v2, v2, v4, vcc
	v_add_u32_e32 v4, 1, v3
	v_cmp_ge_u32_e32 vcc, v2, v1
	s_nop 1
	v_cndmask_b32_e32 v4, v3, v4, vcc
	v_mul_lo_u32 v2, v1, v4
	v_add_u32_e32 v1, v2, v1
	v_cmp_ne_u32_e32 vcc, v5, v1
	v_mov_b64_e32 v[2:3], s[6:7]
	s_and_saveexec_b64 s[4:5], vcc
	s_cbranch_execz .LBB0_685
	v_mov_b32_e32 v4, v1
	v_mov_b32_e32 v1, 0
	global_load_dword v2, v1, s[6:7] sc1
	s_mov_b64 s[20:21], 0
	s_waitcnt vmcnt(0)
	v_cmp_lt_u32_e32 vcc, v2, v4
	s_and_saveexec_b64 s[14:15], vcc
	s_cbranch_execz .LBB0_684
	s_add_u32 s8, s34, 0x200
	s_addc_u32 s9, s35, 0
	s_mov_b32 s11, 1
	s_branch .LBB0_677

; __device__ __forceinline__ unsigned xb_ld(unsigned* p)              { return __hip_atomic_load(p, __ATOMIC_RELAXED, __HIP_MEMORY_SCOPE_AGENT); }
; #define XB_SPIN(cond, bar) do { unsigned _sp = 0; while (cond) { __builtin_amdgcn_s_sleep(1); \
;     if ((++_sp & 255u) == 0u) { if (xb_ld(&(bar)[XB_TMO])) break; if (_sp > XB_SPIN_CAP) { atomicAdd(&(bar)[XB_TMO], 1u); break; } } } } while (0)
; __device__ __forceinline__ void xcd_barrier(const XcdBarrier& b) {
;     ...
;             else XB_SPIN(xb_ld(&bar[XB_TOPGEN]) == tg, bar);
.LBB0_679:
	global_load_dword v2, v1, s[6:7] sc1
	s_add_i32 s11, s11, 1
	s_mov_b64 s[24:25], -1
	s_waitcnt vmcnt(0)
	v_cmp_ge_u32_e32 vcc, v2, v4
	s_orn2_b64 s[28:29], vcc, exec
	s_branch .LBB0_676
